# nt hint on P0's read-once f32 weight loads as well (on v73)
# speedup vs baseline: 1.0016x; 1.0011x over previous
; #define LAS __attribute__((address_space(3)))
; __device__ __forceinline__ unsigned pk2(float lo, float hi) { f32x2 v = {lo, hi}; bf16x2_t b = __builtin_convertvector(v, bf16x2_t); return __builtin_bit_cast(unsigned, b); }
; __device__ __forceinline__ void tr_item(const float* W, int K, int N, bf16_t* WT, int ldt, int rowmode, const float* ksc, LAS float* scr, int item, int lane) {
;     const int nblk = N / 32, kb = item / nblk, nb = item % nblk, k0 = 64 * kb, n0 = 32 * nb;
; #pragma unroll 16
;     for (int i = 0; i < 32; ++i) { const int kk = 2 * i + (lane >> 5); float v = W[(size_t)(k0 + kk) * N + n0 + (lane & 31)]; if (ksc) v *= ksc[k0 + kk]; scr[kk * 33 + (lane & 31)] = v; }
;     asm volatile("s_waitcnt lgkmcnt(0)" ::: "memory");
;     const int c = lane & 7;
; #pragma unroll
;     for (int j = 0; j < 4; ++j) { const int n = n0 + (lane >> 3) + 8 * j; const LAS float* s = scr + (8 * c) * 33 + (lane >> 3) + 8 * j;
;         u32x4 o; o.x = pk2(s[0 * 33], s[1 * 33]); o.y = pk2(s[2 * 33], s[3 * 33]); o.z = pk2(s[4 * 33], s[5 * 33]); o.w = pk2(s[6 * 33], s[7 * 33]);
;         int row = n; if (rowmode) row = (n >> 7) * 256 + (n & 127) + (rowmode == 2 ? 128 : 0);
;         *(u32x4*)(WT + (size_t)row * ldt + k0 + 8 * c) = o; }
;     asm volatile("s_waitcnt lgkmcnt(0)" ::: "memory");
.LBB0_25:
	v_lshl_add_u64 v[38:39], v[34:35], 0, s[18:19]
	global_load_dword v100, v[38:39], off nt
	v_lshl_add_u64 v[38:39], v[32:33], 0, s[18:19]
	global_load_dword v101, v[38:39], off nt
	v_lshl_add_u64 v[38:39], v[30:31], 0, s[18:19]
	global_load_dword v102, v[38:39], off nt
	v_lshl_add_u64 v[38:39], v[28:29], 0, s[18:19]
	global_load_dword v103, v[38:39], off nt
	v_lshl_add_u64 v[38:39], v[26:27], 0, s[18:19]
	global_load_dword v104, v[38:39], off nt
	v_lshl_add_u64 v[38:39], v[24:25], 0, s[18:19]
	global_load_dword v105, v[38:39], off nt
	v_lshl_add_u64 v[38:39], v[22:23], 0, s[18:19]
	global_load_dword v106, v[38:39], off nt
	v_lshl_add_u64 v[38:39], v[20:21], 0, s[18:19]
	global_load_dword v107, v[38:39], off nt
	v_lshl_add_u64 v[38:39], v[18:19], 0, s[18:19]
	global_load_dword v108, v[38:39], off nt
	v_lshl_add_u64 v[38:39], v[16:17], 0, s[18:19]
	global_load_dword v109, v[38:39], off nt
	v_lshl_add_u64 v[38:39], v[14:15], 0, s[18:19]
	global_load_dword v110, v[38:39], off nt
	v_lshl_add_u64 v[38:39], v[12:13], 0, s[18:19]
	global_load_dword v111, v[38:39], off nt
	v_lshl_add_u64 v[38:39], v[10:11], 0, s[18:19]
	global_load_dword v112, v[38:39], off nt
	v_lshl_add_u64 v[38:39], v[8:9], 0, s[18:19]
	global_load_dword v113, v[38:39], off nt
	v_lshl_add_u64 v[38:39], v[6:7], 0, s[18:19]
	global_load_dword v114, v[38:39], off nt
	v_lshl_add_u64 v[38:39], v[4:5], 0, s[18:19]
	s_add_u32 s18, s18, 0x20000
	s_addc_u32 s19, s19, 0
	s_cmp_lg_u32 s18, 0x40000
	global_load_dword v115, v[38:39], off nt
	s_waitcnt vmcnt(15)
	ds_write_b32 v36, v100
	s_waitcnt vmcnt(14)
	ds_write_b32 v36, v101 offset:264
	s_waitcnt vmcnt(13)
	ds_write_b32 v36, v102 offset:528
	s_waitcnt vmcnt(12)
	ds_write_b32 v36, v103 offset:792
	s_waitcnt vmcnt(11)
	ds_write_b32 v36, v104 offset:1056
	s_waitcnt vmcnt(10)
	ds_write_b32 v36, v105 offset:1320
	s_waitcnt vmcnt(9)
	ds_write_b32 v36, v106 offset:1584
	s_waitcnt vmcnt(8)
	ds_write_b32 v36, v107 offset:1848
	s_waitcnt vmcnt(7)
	ds_write_b32 v36, v108 offset:2112
	s_waitcnt vmcnt(6)
	ds_write_b32 v36, v109 offset:2376
	s_waitcnt vmcnt(5)
	ds_write_b32 v36, v110 offset:2640
	s_waitcnt vmcnt(4)
	ds_write_b32 v36, v111 offset:2904
	s_waitcnt vmcnt(3)
	ds_write_b32 v36, v112 offset:3168
	s_waitcnt vmcnt(2)
	ds_write_b32 v36, v113 offset:3432
	s_waitcnt vmcnt(1)
	ds_write_b32 v36, v114 offset:3696
	s_waitcnt vmcnt(0)
	ds_write_b32 v36, v115 offset:3960
	v_add_u32_e32 v36, 0x1080, v36
	s_cbranch_scc1 .LBB0_25
	v_ashrrev_i32_e32 v4, 3, v2
	v_lshlrev_b32_e32 v2, 3, v2
	v_and_b32_e32 v2, 56, v2
	s_and_b64 s[4:5], s[4:5], exec
	v_add_u32_e32 v28, s10, v4
	v_mul_u32_u24_e32 v5, 0x84, v2
	v_lshlrev_b32_e32 v4, 2, v4
	s_cselect_b32 s4, 0x580000, 0
	s_waitcnt lgkmcnt(0)
	v_add3_u32 v29, s3, v5, v4
	s_add_u32 s11, s38, s4
	ds_read2_b32 v[8:9], v29 offset0:33 offset1:41
	ds_read2_b32 v[10:11], v29 offset1:8
	ds_read2_b32 v[12:13], v29 offset0:66 offset1:74
	ds_read2_b32 v[14:15], v29 offset0:99 offset1:107
	ds_read2_b32 v[16:17], v29 offset0:132 offset1:140
	ds_read2_b32 v[18:19], v29 offset0:165 offset1:173
	ds_read2_b32 v[20:21], v29 offset0:198 offset1:206
	ds_read2_b32 v[22:23], v29 offset0:231 offset1:239
	s_addc_u32 s14, s39, 0
	s_lshl_b64 s[4:5], s[8:9], 1
	s_add_u32 s4, s11, s4
	s_addc_u32 s5, s14, s5
	v_lshlrev_b32_e32 v2, 1, v2
	v_lshl_add_u64 v[24:25], s[4:5], 0, v[2:3]
	s_waitcnt lgkmcnt(6)
	v_cvt_pk_bf16_f32 v4, v10, v8
	s_waitcnt lgkmcnt(4)
	v_cvt_pk_bf16_f32 v5, v12, v14
	s_waitcnt lgkmcnt(2)
	v_cvt_pk_bf16_f32 v6, v16, v18
	s_waitcnt lgkmcnt(0)
	v_cvt_pk_bf16_f32 v7, v20, v22
	v_mad_i64_i32 v[26:27], s[4:5], v28, s56, v[24:25]
	v_add_u32_e32 v2, 8, v28
	global_store_dwordx4 v[26:27], v[4:7], off
	s_nop 1
	v_cvt_pk_bf16_f32 v4, v11, v9
	v_cvt_pk_bf16_f32 v5, v13, v15
	v_cvt_pk_bf16_f32 v6, v17, v19
	v_cvt_pk_bf16_f32 v7, v21, v23
	v_mad_i64_i32 v[8:9], s[4:5], v2, s56, v[24:25]
	global_store_dwordx4 v[8:9], v[4:7], off
	ds_read2_b32 v[8:9], v29 offset0:49 offset1:57
	ds_read2_b32 v[10:11], v29 offset0:16 offset1:24
	ds_read2_b32 v[12:13], v29 offset0:82 offset1:90
	ds_read2_b32 v[14:15], v29 offset0:115 offset1:123
	ds_read2_b32 v[16:17], v29 offset0:148 offset1:156
	ds_read2_b32 v[18:19], v29 offset0:181 offset1:189
	ds_read2_b32 v[20:21], v29 offset0:214 offset1:222
	ds_read2_b32 v[22:23], v29 offset0:247 offset1:255
	v_add_u32_e32 v2, 16, v28
	s_waitcnt lgkmcnt(6)
	v_cvt_pk_bf16_f32 v4, v10, v8
	s_waitcnt lgkmcnt(4)
	v_cvt_pk_bf16_f32 v5, v12, v14
	s_waitcnt lgkmcnt(2)
	v_cvt_pk_bf16_f32 v6, v16, v18
	s_waitcnt lgkmcnt(0)
	v_cvt_pk_bf16_f32 v7, v20, v22
	v_mad_i64_i32 v[26:27], s[4:5], v2, s56, v[24:25]
	v_add_u32_e32 v2, 24, v28
	global_store_dwordx4 v[26:27], v[4:7], off
	s_nop 1
	v_cvt_pk_bf16_f32 v4, v11, v9
	v_cvt_pk_bf16_f32 v5, v13, v15
	v_cvt_pk_bf16_f32 v6, v17, v19
	v_cvt_pk_bf16_f32 v7, v21, v23
	v_mad_i64_i32 v[8:9], s[4:5], v2, s56, v[24:25]
	global_store_dwordx4 v[8:9], v[4:7], off
	s_waitcnt lgkmcnt(0)
	s_mov_b64 s[4:5], 0

; #define LAS __attribute__((address_space(3)))
; __device__ __forceinline__ unsigned pk2(float lo, float hi) { f32x2 v = {lo, hi}; bf16x2_t b = __builtin_convertvector(v, bf16x2_t); return __builtin_bit_cast(unsigned, b); }
; __device__ __forceinline__ void tr_item(const float* W, int K, int N, bf16_t* WT, int ldt, int rowmode, const float* ksc, LAS float* scr, int item, int lane) {
;     const int nblk = N / 32, kb = item / nblk, nb = item % nblk, k0 = 64 * kb, n0 = 32 * nb;
; #pragma unroll 16
;     for (int i = 0; i < 32; ++i) { const int kk = 2 * i + (lane >> 5); float v = W[(size_t)(k0 + kk) * N + n0 + (lane & 31)]; if (ksc) v *= ksc[k0 + kk]; scr[kk * 33 + (lane & 31)] = v; }
;     asm volatile("s_waitcnt lgkmcnt(0)" ::: "memory");
;     const int c = lane & 7;
; #pragma unroll
;     for (int j = 0; j < 4; ++j) { const int n = n0 + (lane >> 3) + 8 * j; const LAS float* s = scr + (8 * c) * 33 + (lane >> 3) + 8 * j;
;         u32x4 o; o.x = pk2(s[0 * 33], s[1 * 33]); o.y = pk2(s[2 * 33], s[3 * 33]); o.z = pk2(s[4 * 33], s[5 * 33]); o.w = pk2(s[6 * 33], s[7 * 33]);
;         int row = n; if (rowmode) row = (n >> 7) * 256 + (n & 127) + (rowmode == 2 ? 128 : 0);
;         *(u32x4*)(WT + (size_t)row * ldt + k0 + 8 * c) = o; }
;     asm volatile("s_waitcnt lgkmcnt(0)" ::: "memory");
.LBB0_29:
	v_lshl_add_u64 v[38:39], v[34:35], 0, s[10:11]
	global_load_dword v100, v[38:39], off nt
	v_lshl_add_u64 v[38:39], v[32:33], 0, s[10:11]
	global_load_dword v101, v[38:39], off nt
	v_lshl_add_u64 v[38:39], v[30:31], 0, s[10:11]
	global_load_dword v102, v[38:39], off nt
	v_lshl_add_u64 v[38:39], v[28:29], 0, s[10:11]
	global_load_dword v103, v[38:39], off nt
	v_lshl_add_u64 v[38:39], v[26:27], 0, s[10:11]
	global_load_dword v104, v[38:39], off nt
	v_lshl_add_u64 v[38:39], v[24:25], 0, s[10:11]
	global_load_dword v105, v[38:39], off nt
	v_lshl_add_u64 v[38:39], v[22:23], 0, s[10:11]
	global_load_dword v106, v[38:39], off nt
	v_lshl_add_u64 v[38:39], v[20:21], 0, s[10:11]
	global_load_dword v107, v[38:39], off nt
	v_lshl_add_u64 v[38:39], v[18:19], 0, s[10:11]
	global_load_dword v108, v[38:39], off nt
	v_lshl_add_u64 v[38:39], v[16:17], 0, s[10:11]
	global_load_dword v109, v[38:39], off nt
	v_lshl_add_u64 v[38:39], v[14:15], 0, s[10:11]
	global_load_dword v110, v[38:39], off nt
	v_lshl_add_u64 v[38:39], v[12:13], 0, s[10:11]
	global_load_dword v111, v[38:39], off nt
	v_lshl_add_u64 v[38:39], v[10:11], 0, s[10:11]
	global_load_dword v112, v[38:39], off nt
	v_lshl_add_u64 v[38:39], v[8:9], 0, s[10:11]
	global_load_dword v113, v[38:39], off nt
	v_lshl_add_u64 v[38:39], v[6:7], 0, s[10:11]
	global_load_dword v114, v[38:39], off nt
	v_lshl_add_u64 v[38:39], v[4:5], 0, s[10:11]
	s_add_u32 s10, s10, 0x58000
	s_addc_u32 s11, s11, 0
	s_cmp_lg_u32 s10, 0xb0000
	global_load_dword v115, v[38:39], off nt
	s_waitcnt vmcnt(15)
	ds_write_b32 v36, v100
	s_waitcnt vmcnt(14)
	ds_write_b32 v36, v101 offset:264
	s_waitcnt vmcnt(13)
	ds_write_b32 v36, v102 offset:528
	s_waitcnt vmcnt(12)
	ds_write_b32 v36, v103 offset:792
	s_waitcnt vmcnt(11)
	ds_write_b32 v36, v104 offset:1056
	s_waitcnt vmcnt(10)
	ds_write_b32 v36, v105 offset:1320
	s_waitcnt vmcnt(9)
	ds_write_b32 v36, v106 offset:1584
	s_waitcnt vmcnt(8)
	ds_write_b32 v36, v107 offset:1848
	s_waitcnt vmcnt(7)
	ds_write_b32 v36, v108 offset:2112
	s_waitcnt vmcnt(6)
	ds_write_b32 v36, v109 offset:2376
	s_waitcnt vmcnt(5)
	ds_write_b32 v36, v110 offset:2640
	s_waitcnt vmcnt(4)
	ds_write_b32 v36, v111 offset:2904
	s_waitcnt vmcnt(3)
	ds_write_b32 v36, v112 offset:3168
	s_waitcnt vmcnt(2)
	ds_write_b32 v36, v113 offset:3432
	s_waitcnt vmcnt(1)
	ds_write_b32 v36, v114 offset:3696
	s_waitcnt vmcnt(0)
	ds_write_b32 v36, v115 offset:3960
	v_add_u32_e32 v36, 0x1080, v36
	s_cbranch_scc1 .LBB0_29
	s_lshr_b32 s9, s18, 1
	s_mul_i32 s9, s9, 0xb00000
	s_add_u32 s9, s36, s9
	v_ashrrev_i32_e32 v4, 3, v2
	v_lshlrev_b32_e32 v2, 3, v2
	s_addc_u32 s10, s37, 0
	v_add_u32_e32 v28, s8, v4
	v_and_b32_e32 v2, 56, v2
	s_lshl_b32 s8, s14, 7
	s_lshl_b64 s[4:5], s[4:5], 1
	v_mul_u32_u24_e32 v5, 0x84, v2
	v_lshlrev_b32_e32 v4, 2, v4
	s_add_u32 s4, s9, s4
	s_waitcnt lgkmcnt(0)
	v_add3_u32 v29, s3, v5, v4
	s_addc_u32 s5, s10, s5
	v_lshlrev_b32_e32 v2, 1, v2
	ds_read2_b32 v[8:9], v29 offset0:33 offset1:41
	ds_read2_b32 v[10:11], v29 offset1:8
	ds_read2_b32 v[12:13], v29 offset0:66 offset1:74
	ds_read2_b32 v[14:15], v29 offset0:99 offset1:107
	ds_read2_b32 v[16:17], v29 offset0:132 offset1:140
	ds_read2_b32 v[18:19], v29 offset0:165 offset1:173
	ds_read2_b32 v[20:21], v29 offset0:198 offset1:206
	ds_read2_b32 v[22:23], v29 offset0:231 offset1:239
	v_lshl_add_u64 v[24:25], s[4:5], 0, v[2:3]
	v_lshlrev_b32_e32 v2, 1, v28
	s_waitcnt lgkmcnt(6)
	v_cvt_pk_bf16_f32 v4, v10, v8
	v_and_b32_e32 v2, 0xffffff00, v2
	v_and_b32_e32 v8, 0x7f, v28
	v_or3_b32 v26, v8, v2, s8
	v_add_u32_e32 v2, 8, v28
	v_ashrrev_i32_e32 v27, 31, v26
	v_lshlrev_b32_e32 v8, 1, v2
	v_lshlrev_b64 v[26:27], 11, v[26:27]
	v_and_b32_e32 v8, 0xffffff00, v8
	v_and_b32_e32 v2, 0x7f, v2
	s_waitcnt lgkmcnt(4)
	v_cvt_pk_bf16_f32 v5, v12, v14
	s_waitcnt lgkmcnt(2)
	v_cvt_pk_bf16_f32 v6, v16, v18
	s_waitcnt lgkmcnt(0)
	v_cvt_pk_bf16_f32 v7, v20, v22
	v_lshl_add_u64 v[26:27], v[24:25], 0, v[26:27]
	v_or3_b32 v8, v2, v8, s8
	global_store_dwordx4 v[26:27], v[4:7], off
	v_add_u32_e32 v2, 16, v28
	s_nop 0
	v_cvt_pk_bf16_f32 v4, v11, v9
	v_ashrrev_i32_e32 v9, 31, v8
	v_lshlrev_b64 v[8:9], 11, v[8:9]
	v_cvt_pk_bf16_f32 v5, v13, v15
	v_cvt_pk_bf16_f32 v6, v17, v19
	v_cvt_pk_bf16_f32 v7, v21, v23
	v_lshl_add_u64 v[8:9], v[24:25], 0, v[8:9]
	global_store_dwordx4 v[8:9], v[4:7], off
	ds_read2_b32 v[8:9], v29 offset0:16 offset1:24
	ds_read2_b32 v[10:11], v29 offset0:49 offset1:57
	ds_read2_b32 v[12:13], v29 offset0:82 offset1:90
	ds_read2_b32 v[14:15], v29 offset0:115 offset1:123
	ds_read2_b32 v[16:17], v29 offset0:148 offset1:156
	ds_read2_b32 v[18:19], v29 offset0:181 offset1:189
	ds_read2_b32 v[20:21], v29 offset0:214 offset1:222
	ds_read2_b32 v[22:23], v29 offset0:247 offset1:255
	s_waitcnt lgkmcnt(6)
	v_cvt_pk_bf16_f32 v4, v8, v10
	v_lshlrev_b32_e32 v8, 1, v2
	v_and_b32_e32 v8, 0xffffff00, v8
	v_and_b32_e32 v2, 0x7f, v2
	v_or3_b32 v26, v2, v8, s8
	v_add_u32_e32 v2, 24, v28
	v_ashrrev_i32_e32 v27, 31, v26
	v_lshlrev_b32_e32 v8, 1, v2
	v_lshlrev_b64 v[26:27], 11, v[26:27]
	v_and_b32_e32 v8, 0xffffff00, v8
	v_and_b32_e32 v2, 0x7f, v2
	s_waitcnt lgkmcnt(4)
	v_cvt_pk_bf16_f32 v5, v12, v14
	s_waitcnt lgkmcnt(2)
	v_cvt_pk_bf16_f32 v6, v16, v18
	s_waitcnt lgkmcnt(0)
	v_cvt_pk_bf16_f32 v7, v20, v22
	v_lshl_add_u64 v[26:27], v[24:25], 0, v[26:27]
	v_or3_b32 v8, v2, v8, s8
	global_store_dwordx4 v[26:27], v[4:7], off
	s_nop 1
	v_cvt_pk_bf16_f32 v4, v9, v11
	v_ashrrev_i32_e32 v9, 31, v8
	v_lshlrev_b64 v[8:9], 11, v[8:9]
	v_cvt_pk_bf16_f32 v5, v13, v15
	v_cvt_pk_bf16_f32 v6, v17, v19
	v_cvt_pk_bf16_f32 v7, v21, v23
	v_lshl_add_u64 v[8:9], v[24:25], 0, v[8:9]
	global_store_dwordx4 v[8:9], v[4:7], off
	s_waitcnt lgkmcnt(0)

; #define LAS __attribute__((address_space(3)))
; __device__ __forceinline__ unsigned pk2(float lo, float hi) { f32x2 v = {lo, hi}; bf16x2_t b = __builtin_convertvector(v, bf16x2_t); return __builtin_bit_cast(unsigned, b); }
; __device__ __forceinline__ void tr_item(const float* W, int K, int N, bf16_t* WT, int ldt, int rowmode, const float* ksc, LAS float* scr, int item, int lane) {
;     const int nblk = N / 32, kb = item / nblk, nb = item % nblk, k0 = 64 * kb, n0 = 32 * nb;
; #pragma unroll 16
;     for (int i = 0; i < 32; ++i) { const int kk = 2 * i + (lane >> 5); float v = W[(size_t)(k0 + kk) * N + n0 + (lane & 31)]; if (ksc) v *= ksc[k0 + kk]; scr[kk * 33 + (lane & 31)] = v; }
;     asm volatile("s_waitcnt lgkmcnt(0)" ::: "memory");
;     const int c = lane & 7;
; #pragma unroll
;     for (int j = 0; j < 4; ++j) { const int n = n0 + (lane >> 3) + 8 * j; const LAS float* s = scr + (8 * c) * 33 + (lane >> 3) + 8 * j;
;         u32x4 o; o.x = pk2(s[0 * 33], s[1 * 33]); o.y = pk2(s[2 * 33], s[3 * 33]); o.z = pk2(s[4 * 33], s[5 * 33]); o.w = pk2(s[6 * 33], s[7 * 33]);
;         int row = n; if (rowmode) row = (n >> 7) * 256 + (n & 127) + (rowmode == 2 ? 128 : 0);
;         *(u32x4*)(WT + (size_t)row * ldt + k0 + 8 * c) = o; }
;     asm volatile("s_waitcnt lgkmcnt(0)" ::: "memory");
.LBB0_34:
	v_lshl_add_u64 v[38:39], v[34:35], 0, s[4:5]
	global_load_dword v100, v[38:39], off nt
	v_lshl_add_u64 v[38:39], v[32:33], 0, s[4:5]
	global_load_dword v101, v[38:39], off nt
	v_lshl_add_u64 v[38:39], v[30:31], 0, s[4:5]
	global_load_dword v102, v[38:39], off nt
	v_lshl_add_u64 v[38:39], v[28:29], 0, s[4:5]
	global_load_dword v103, v[38:39], off nt
	v_lshl_add_u64 v[38:39], v[26:27], 0, s[4:5]
	global_load_dword v104, v[38:39], off nt
	v_lshl_add_u64 v[38:39], v[24:25], 0, s[4:5]
	global_load_dword v105, v[38:39], off nt
	v_lshl_add_u64 v[38:39], v[22:23], 0, s[4:5]
	global_load_dword v106, v[38:39], off nt
	v_lshl_add_u64 v[38:39], v[20:21], 0, s[4:5]
	global_load_dword v107, v[38:39], off nt
	v_lshl_add_u64 v[38:39], v[18:19], 0, s[4:5]
	global_load_dword v108, v[38:39], off nt
	v_lshl_add_u64 v[38:39], v[16:17], 0, s[4:5]
	global_load_dword v109, v[38:39], off nt
	v_lshl_add_u64 v[38:39], v[14:15], 0, s[4:5]
	global_load_dword v110, v[38:39], off nt
	v_lshl_add_u64 v[38:39], v[12:13], 0, s[4:5]
	global_load_dword v111, v[38:39], off nt
	v_lshl_add_u64 v[38:39], v[10:11], 0, s[4:5]
	global_load_dword v112, v[38:39], off nt
	v_lshl_add_u64 v[38:39], v[8:9], 0, s[4:5]
	global_load_dword v113, v[38:39], off nt
	v_lshl_add_u64 v[38:39], v[6:7], 0, s[4:5]
	global_load_dword v114, v[38:39], off nt
	v_lshl_add_u64 v[38:39], v[4:5], 0, s[4:5]
	s_add_u32 s4, s4, 0x20000
	s_addc_u32 s5, s5, 0
	s_cmp_lg_u32 s4, 0x40000
	global_load_dword v115, v[38:39], off nt
	s_waitcnt vmcnt(15)
	ds_write_b32 v37, v100
	s_waitcnt vmcnt(14)
	ds_write_b32 v37, v101 offset:264
	s_waitcnt vmcnt(13)
	ds_write_b32 v37, v102 offset:528
	s_waitcnt vmcnt(12)
	ds_write_b32 v37, v103 offset:792
	s_waitcnt vmcnt(11)
	ds_write_b32 v37, v104 offset:1056
	s_waitcnt vmcnt(10)
	ds_write_b32 v37, v105 offset:1320
	s_waitcnt vmcnt(9)
	ds_write_b32 v37, v106 offset:1584
	s_waitcnt vmcnt(8)
	ds_write_b32 v37, v107 offset:1848
	s_waitcnt vmcnt(7)
	ds_write_b32 v37, v108 offset:2112
	s_waitcnt vmcnt(6)
	ds_write_b32 v37, v109 offset:2376
	s_waitcnt vmcnt(5)
	ds_write_b32 v37, v110 offset:2640
	s_waitcnt vmcnt(4)
	ds_write_b32 v37, v111 offset:2904
	s_waitcnt vmcnt(3)
	ds_write_b32 v37, v112 offset:3168
	s_waitcnt vmcnt(2)
	ds_write_b32 v37, v113 offset:3432
	s_waitcnt vmcnt(1)
	ds_write_b32 v37, v114 offset:3696
	s_waitcnt vmcnt(0)
	ds_write_b32 v37, v115 offset:3960
	v_add_u32_e32 v37, 0x1080, v37
	s_cbranch_scc1 .LBB0_34
	s_lshl_b32 s5, s1, 5
	v_lshlrev_b32_e32 v4, 3, v36
	s_and_b32 s5, s5, 0x3e0
	v_ashrrev_i32_e32 v2, 3, v36
	v_and_b32_e32 v4, 56, v4
	s_lshl_b32 s4, s1, 1
	v_add_u32_e32 v8, s5, v2
	v_mul_u32_u24_e32 v5, 0x84, v4
	v_lshlrev_b32_e32 v2, 2, v2
	s_add_i32 s4, s4, 0x1e040
	s_waitcnt lgkmcnt(0)
	v_add3_u32 v28, s3, v5, v2
	s_and_b32 s4, s4, 0x1ffc0
	ds_read2_b32 v[10:11], v28 offset0:33 offset1:41
	ds_read2_b32 v[12:13], v28 offset1:8
	ds_read2_b32 v[14:15], v28 offset0:66 offset1:74
	ds_read2_b32 v[16:17], v28 offset0:99 offset1:107
	ds_read2_b32 v[18:19], v28 offset0:132 offset1:140
	ds_read2_b32 v[20:21], v28 offset0:165 offset1:173
	ds_read2_b32 v[22:23], v28 offset0:198 offset1:206
	ds_read2_b32 v[24:25], v28 offset0:231 offset1:239
	s_lshl_b32 s4, s4, 1
	s_add_u32 s4, s34, s4
	s_addc_u32 s5, s35, 0
	v_lshlrev_b32_e32 v2, 1, v4
	v_ashrrev_i32_e32 v9, 31, v8
	v_lshl_add_u64 v[26:27], s[4:5], 0, v[2:3]
	v_lshlrev_b64 v[8:9], 11, v[8:9]
	s_waitcnt lgkmcnt(6)
	v_cvt_pk_bf16_f32 v4, v12, v10
	s_waitcnt lgkmcnt(4)
	v_cvt_pk_bf16_f32 v5, v14, v16
	s_waitcnt lgkmcnt(2)
	v_cvt_pk_bf16_f32 v6, v18, v20
	s_waitcnt lgkmcnt(0)
	v_cvt_pk_bf16_f32 v7, v22, v24
	v_lshl_add_u64 v[8:9], v[26:27], 0, v[8:9]
	global_store_dwordx4 v[8:9], v[4:7], off
	v_add_co_u32_e32 v10, vcc, s59, v8
	s_nop 0
	v_cvt_pk_bf16_f32 v4, v13, v11
	v_cvt_pk_bf16_f32 v5, v15, v17
	v_cvt_pk_bf16_f32 v6, v19, v21
	v_cvt_pk_bf16_f32 v7, v23, v25
	ds_read2_b32 v[12:13], v28 offset0:49 offset1:57
	ds_read2_b32 v[14:15], v28 offset0:16 offset1:24
	ds_read2_b32 v[16:17], v28 offset0:82 offset1:90
	ds_read2_b32 v[18:19], v28 offset0:115 offset1:123
	ds_read2_b32 v[20:21], v28 offset0:148 offset1:156
	ds_read2_b32 v[22:23], v28 offset0:181 offset1:189
	ds_read2_b32 v[24:25], v28 offset0:214 offset1:222
	ds_read2_b32 v[26:27], v28 offset0:247 offset1:255
	v_addc_co_u32_e32 v11, vcc, 0, v9, vcc
	global_store_dwordx4 v[10:11], v[4:7], off
	v_add_co_u32_e32 v10, vcc, s60, v8
	s_waitcnt lgkmcnt(6)
	v_cvt_pk_bf16_f32 v4, v14, v12
	v_addc_co_u32_e32 v11, vcc, 0, v9, vcc
	s_waitcnt lgkmcnt(4)
	v_cvt_pk_bf16_f32 v5, v16, v18
	s_waitcnt lgkmcnt(2)
	v_cvt_pk_bf16_f32 v6, v20, v22
	s_waitcnt lgkmcnt(0)
	v_cvt_pk_bf16_f32 v7, v24, v26
	v_add_co_u32_e32 v8, vcc, 0xc000, v8
	global_store_dwordx4 v[10:11], v[4:7], off
	s_nop 0
	v_addc_co_u32_e32 v9, vcc, 0, v9, vcc
	v_cvt_pk_bf16_f32 v4, v15, v13
	v_cvt_pk_bf16_f32 v5, v17, v19
	v_cvt_pk_bf16_f32 v6, v21, v23
	v_cvt_pk_bf16_f32 v7, v25, v27
	global_store_dwordx4 v[8:9], v[4:7], off
	s_waitcnt lgkmcnt(0)

; #define LAS __attribute__((address_space(3)))
; __device__ __forceinline__ unsigned pk2(float lo, float hi) { f32x2 v = {lo, hi}; bf16x2_t b = __builtin_convertvector(v, bf16x2_t); return __builtin_bit_cast(unsigned, b); }
; __device__ __forceinline__ void tr_item(const float* W, int K, int N, bf16_t* WT, int ldt, int rowmode, const float* ksc, LAS float* scr, int item, int lane) {
;     const int nblk = N / 32, kb = item / nblk, nb = item % nblk, k0 = 64 * kb, n0 = 32 * nb;
; #pragma unroll 16
;     for (int i = 0; i < 32; ++i) { const int kk = 2 * i + (lane >> 5); float v = W[(size_t)(k0 + kk) * N + n0 + (lane & 31)]; if (ksc) v *= ksc[k0 + kk]; scr[kk * 33 + (lane & 31)] = v; }
;     asm volatile("s_waitcnt lgkmcnt(0)" ::: "memory");
;     const int c = lane & 7;
; #pragma unroll
;     for (int j = 0; j < 4; ++j) { const int n = n0 + (lane >> 3) + 8 * j; const LAS float* s = scr + (8 * c) * 33 + (lane >> 3) + 8 * j;
;         u32x4 o; o.x = pk2(s[0 * 33], s[1 * 33]); o.y = pk2(s[2 * 33], s[3 * 33]); o.z = pk2(s[4 * 33], s[5 * 33]); o.w = pk2(s[6 * 33], s[7 * 33]);
;         int row = n; if (rowmode) row = (n >> 7) * 256 + (n & 127) + (rowmode == 2 ? 128 : 0);
;         *(u32x4*)(WT + (size_t)row * ldt + k0 + 8 * c) = o; }
;     asm volatile("s_waitcnt lgkmcnt(0)" ::: "memory");
.LBB0_39:
	v_lshl_add_u64 v[38:39], v[34:35], 0, s[4:5]
	global_load_dword v100, v[38:39], off nt
	v_lshl_add_u64 v[38:39], v[32:33], 0, s[4:5]
	global_load_dword v101, v[38:39], off nt
	v_lshl_add_u64 v[38:39], v[30:31], 0, s[4:5]
	global_load_dword v102, v[38:39], off nt
	v_lshl_add_u64 v[38:39], v[28:29], 0, s[4:5]
	global_load_dword v103, v[38:39], off nt
	v_lshl_add_u64 v[38:39], v[26:27], 0, s[4:5]
	global_load_dword v104, v[38:39], off nt
	v_lshl_add_u64 v[38:39], v[24:25], 0, s[4:5]
	global_load_dword v105, v[38:39], off nt
	v_lshl_add_u64 v[38:39], v[22:23], 0, s[4:5]
	global_load_dword v106, v[38:39], off nt
	v_lshl_add_u64 v[38:39], v[20:21], 0, s[4:5]
	global_load_dword v107, v[38:39], off nt
	v_lshl_add_u64 v[38:39], v[18:19], 0, s[4:5]
	global_load_dword v108, v[38:39], off nt
	v_lshl_add_u64 v[38:39], v[16:17], 0, s[4:5]
	global_load_dword v109, v[38:39], off nt
	v_lshl_add_u64 v[38:39], v[14:15], 0, s[4:5]
	global_load_dword v110, v[38:39], off nt
	v_lshl_add_u64 v[38:39], v[12:13], 0, s[4:5]
	global_load_dword v111, v[38:39], off nt
	v_lshl_add_u64 v[38:39], v[10:11], 0, s[4:5]
	global_load_dword v112, v[38:39], off nt
	v_lshl_add_u64 v[38:39], v[8:9], 0, s[4:5]
	global_load_dword v113, v[38:39], off nt
	v_lshl_add_u64 v[38:39], v[6:7], 0, s[4:5]
	global_load_dword v114, v[38:39], off nt
	v_lshl_add_u64 v[38:39], v[4:5], 0, s[4:5]
	s_add_u32 s4, s4, 0x80000
	s_addc_u32 s5, s5, 0
	s_cmp_lg_u32 s4, 0x100000
	global_load_dword v115, v[38:39], off nt
	s_waitcnt vmcnt(15)
	ds_write_b32 v36, v100
	s_waitcnt vmcnt(14)
	ds_write_b32 v36, v101 offset:264
	s_waitcnt vmcnt(13)
	ds_write_b32 v36, v102 offset:528
	s_waitcnt vmcnt(12)
	ds_write_b32 v36, v103 offset:792
	s_waitcnt vmcnt(11)
	ds_write_b32 v36, v104 offset:1056
	s_waitcnt vmcnt(10)
	ds_write_b32 v36, v105 offset:1320
	s_waitcnt vmcnt(9)
	ds_write_b32 v36, v106 offset:1584
	s_waitcnt vmcnt(8)
	ds_write_b32 v36, v107 offset:1848
	s_waitcnt vmcnt(7)
	ds_write_b32 v36, v108 offset:2112
	s_waitcnt vmcnt(6)
	ds_write_b32 v36, v109 offset:2376
	s_waitcnt vmcnt(5)
	ds_write_b32 v36, v110 offset:2640
	s_waitcnt vmcnt(4)
	ds_write_b32 v36, v111 offset:2904
	s_waitcnt vmcnt(3)
	ds_write_b32 v36, v112 offset:3168
	s_waitcnt vmcnt(2)
	ds_write_b32 v36, v113 offset:3432
	s_waitcnt vmcnt(1)
	ds_write_b32 v36, v114 offset:3696
	s_waitcnt vmcnt(0)
	ds_write_b32 v36, v115 offset:3960
	v_add_u32_e32 v36, 0x1080, v36
	s_cbranch_scc1 .LBB0_39
	s_add_i32 s4, s1, 0xfffff820
	s_lshl_b32 s5, s4, 5
	v_ashrrev_i32_e32 v4, 3, v2
	v_lshlrev_b32_e32 v2, 3, v2
	s_and_b32 s5, s5, 0xfe0
	v_and_b32_e32 v2, 56, v2
	v_add_u32_e32 v8, s5, v4
	v_mul_u32_u24_e32 v5, 0x84, v2
	v_lshlrev_b32_e32 v4, 2, v4
	s_waitcnt lgkmcnt(0)
	v_add3_u32 v28, s3, v5, v4
	ds_read2_b32 v[10:11], v28 offset0:33 offset1:41
	ds_read2_b32 v[12:13], v28 offset1:8
	ds_read2_b32 v[14:15], v28 offset0:66 offset1:74
	ds_read2_b32 v[16:17], v28 offset0:99 offset1:107
	ds_read2_b32 v[18:19], v28 offset0:132 offset1:140
	ds_read2_b32 v[20:21], v28 offset0:165 offset1:173
	ds_read2_b32 v[22:23], v28 offset0:198 offset1:206
	ds_read2_b32 v[24:25], v28 offset0:231 offset1:239
	s_and_b32 s4, s4, 0xff80
	s_add_u32 s4, s31, s4
	s_addc_u32 s5, s33, 0
	v_lshlrev_b32_e32 v2, 1, v2
	v_ashrrev_i32_e32 v9, 31, v8
	v_lshl_add_u64 v[26:27], s[4:5], 0, v[2:3]
	v_lshlrev_b64 v[8:9], 11, v[8:9]
	s_waitcnt lgkmcnt(6)
	v_cvt_pk_bf16_f32 v4, v12, v10
	s_waitcnt lgkmcnt(4)
	v_cvt_pk_bf16_f32 v5, v14, v16
	s_waitcnt lgkmcnt(2)
	v_cvt_pk_bf16_f32 v6, v18, v20
	s_waitcnt lgkmcnt(0)
	v_cvt_pk_bf16_f32 v7, v22, v24
	v_lshl_add_u64 v[8:9], v[26:27], 0, v[8:9]
	global_store_dwordx4 v[8:9], v[4:7], off
	v_add_co_u32_e32 v10, vcc, s59, v8
	s_nop 0
	v_cvt_pk_bf16_f32 v4, v13, v11
	v_cvt_pk_bf16_f32 v5, v15, v17
	v_cvt_pk_bf16_f32 v6, v19, v21
	v_cvt_pk_bf16_f32 v7, v23, v25
	ds_read2_b32 v[12:13], v28 offset0:49 offset1:57
	ds_read2_b32 v[14:15], v28 offset0:16 offset1:24
	ds_read2_b32 v[16:17], v28 offset0:82 offset1:90
	ds_read2_b32 v[18:19], v28 offset0:115 offset1:123
	ds_read2_b32 v[20:21], v28 offset0:148 offset1:156
	ds_read2_b32 v[22:23], v28 offset0:181 offset1:189
	ds_read2_b32 v[24:25], v28 offset0:214 offset1:222
	ds_read2_b32 v[26:27], v28 offset0:247 offset1:255
	v_addc_co_u32_e32 v11, vcc, 0, v9, vcc
	global_store_dwordx4 v[10:11], v[4:7], off
	v_add_co_u32_e32 v10, vcc, s60, v8
	s_waitcnt lgkmcnt(6)
	v_cvt_pk_bf16_f32 v4, v14, v12
	v_addc_co_u32_e32 v11, vcc, 0, v9, vcc
	s_waitcnt lgkmcnt(4)
	v_cvt_pk_bf16_f32 v5, v16, v18
	s_waitcnt lgkmcnt(2)
	v_cvt_pk_bf16_f32 v6, v20, v22
	s_waitcnt lgkmcnt(0)
	v_cvt_pk_bf16_f32 v7, v24, v26
	v_add_co_u32_e32 v8, vcc, 0xc000, v8
	global_store_dwordx4 v[10:11], v[4:7], off
	s_nop 0
	v_addc_co_u32_e32 v9, vcc, 0, v9, vcc
	v_cvt_pk_bf16_f32 v4, v15, v13
	v_cvt_pk_bf16_f32 v5, v17, v19
	v_cvt_pk_bf16_f32 v6, v21, v23
	v_cvt_pk_bf16_f32 v7, v25, v27
	global_store_dwordx4 v[8:9], v[4:7], off
	s_waitcnt lgkmcnt(0)

; #define LAS __attribute__((address_space(3)))
; __device__ __forceinline__ unsigned pk2(float lo, float hi) { f32x2 v = {lo, hi}; bf16x2_t b = __builtin_convertvector(v, bf16x2_t); return __builtin_bit_cast(unsigned, b); }
; __device__ __forceinline__ void tr_item(const float* W, int K, int N, bf16_t* WT, int ldt, int rowmode, const float* ksc, LAS float* scr, int item, int lane) {
;     const int nblk = N / 32, kb = item / nblk, nb = item % nblk, k0 = 64 * kb, n0 = 32 * nb;
; #pragma unroll 16
;     for (int i = 0; i < 32; ++i) { const int kk = 2 * i + (lane >> 5); float v = W[(size_t)(k0 + kk) * N + n0 + (lane & 31)]; if (ksc) v *= ksc[k0 + kk]; scr[kk * 33 + (lane & 31)] = v; }
;     asm volatile("s_waitcnt lgkmcnt(0)" ::: "memory");
;     const int c = lane & 7;
; #pragma unroll
;     for (int j = 0; j < 4; ++j) { const int n = n0 + (lane >> 3) + 8 * j; const LAS float* s = scr + (8 * c) * 33 + (lane >> 3) + 8 * j;
;         u32x4 o; o.x = pk2(s[0 * 33], s[1 * 33]); o.y = pk2(s[2 * 33], s[3 * 33]); o.z = pk2(s[4 * 33], s[5 * 33]); o.w = pk2(s[6 * 33], s[7 * 33]);
;         int row = n; if (rowmode) row = (n >> 7) * 256 + (n & 127) + (rowmode == 2 ? 128 : 0);
;         *(u32x4*)(WT + (size_t)row * ldt + k0 + 8 * c) = o; }
;     asm volatile("s_waitcnt lgkmcnt(0)" ::: "memory");
.LBB0_44:
	v_lshl_add_u64 v[38:39], v[34:35], 0, s[4:5]
	global_load_dword v100, v[38:39], off nt
	v_lshl_add_u64 v[38:39], v[32:33], 0, s[4:5]
	global_load_dword v101, v[38:39], off nt
	v_lshl_add_u64 v[38:39], v[30:31], 0, s[4:5]
	global_load_dword v102, v[38:39], off nt
	v_lshl_add_u64 v[38:39], v[28:29], 0, s[4:5]
	global_load_dword v103, v[38:39], off nt
	v_lshl_add_u64 v[38:39], v[26:27], 0, s[4:5]
	global_load_dword v104, v[38:39], off nt
	v_lshl_add_u64 v[38:39], v[24:25], 0, s[4:5]
	global_load_dword v105, v[38:39], off nt
	v_lshl_add_u64 v[38:39], v[22:23], 0, s[4:5]
	global_load_dword v106, v[38:39], off nt
	v_lshl_add_u64 v[38:39], v[20:21], 0, s[4:5]
	global_load_dword v107, v[38:39], off nt
	v_lshl_add_u64 v[38:39], v[18:19], 0, s[4:5]
	global_load_dword v108, v[38:39], off nt
	v_lshl_add_u64 v[38:39], v[16:17], 0, s[4:5]
	global_load_dword v109, v[38:39], off nt
	v_lshl_add_u64 v[38:39], v[14:15], 0, s[4:5]
	global_load_dword v110, v[38:39], off nt
	v_lshl_add_u64 v[38:39], v[12:13], 0, s[4:5]
	global_load_dword v111, v[38:39], off nt
	v_lshl_add_u64 v[38:39], v[10:11], 0, s[4:5]
	global_load_dword v112, v[38:39], off nt
	v_lshl_add_u64 v[38:39], v[8:9], 0, s[4:5]
	global_load_dword v113, v[38:39], off nt
	v_lshl_add_u64 v[38:39], v[6:7], 0, s[4:5]
	global_load_dword v114, v[38:39], off nt
	v_lshl_add_u64 v[38:39], v[4:5], 0, s[4:5]
	s_add_u32 s4, s4, 0x20000
	s_addc_u32 s5, s5, 0
	s_cmp_lg_u32 s4, 0x40000
	global_load_dword v115, v[38:39], off nt
	s_waitcnt vmcnt(15)
	ds_write_b32 v37, v100
	s_waitcnt vmcnt(14)
	ds_write_b32 v37, v101 offset:264
	s_waitcnt vmcnt(13)
	ds_write_b32 v37, v102 offset:528
	s_waitcnt vmcnt(12)
	ds_write_b32 v37, v103 offset:792
	s_waitcnt vmcnt(11)
	ds_write_b32 v37, v104 offset:1056
	s_waitcnt vmcnt(10)
	ds_write_b32 v37, v105 offset:1320
	s_waitcnt vmcnt(9)
	ds_write_b32 v37, v106 offset:1584
	s_waitcnt vmcnt(8)
	ds_write_b32 v37, v107 offset:1848
	s_waitcnt vmcnt(7)
	ds_write_b32 v37, v108 offset:2112
	s_waitcnt vmcnt(6)
	ds_write_b32 v37, v109 offset:2376
	s_waitcnt vmcnt(5)
	ds_write_b32 v37, v110 offset:2640
	s_waitcnt vmcnt(4)
	ds_write_b32 v37, v111 offset:2904
	s_waitcnt vmcnt(3)
	ds_write_b32 v37, v112 offset:3168
	s_waitcnt vmcnt(2)
	ds_write_b32 v37, v113 offset:3432
	s_waitcnt vmcnt(1)
	ds_write_b32 v37, v114 offset:3696
	s_waitcnt vmcnt(0)
	ds_write_b32 v37, v115 offset:3960
	v_add_u32_e32 v37, 0x1080, v37
	s_cbranch_scc1 .LBB0_44
	s_lshl_b32 s5, s1, 5
	v_lshlrev_b32_e32 v4, 3, v36
	s_and_b32 s5, s5, 0x3e0
	v_ashrrev_i32_e32 v2, 3, v36
	v_and_b32_e32 v4, 56, v4
	s_lshl_b32 s4, s1, 1
	v_add_u32_e32 v8, s5, v2
	v_mul_u32_u24_e32 v5, 0x84, v4
	v_lshlrev_b32_e32 v2, 2, v2
	s_add_i32 s4, s4, 0x1f440
	s_waitcnt lgkmcnt(0)
	v_add3_u32 v28, s3, v5, v2
	s_and_b32 s4, s4, 0x1ffc0
	ds_read2_b32 v[10:11], v28 offset0:33 offset1:41
	ds_read2_b32 v[12:13], v28 offset1:8
	ds_read2_b32 v[14:15], v28 offset0:66 offset1:74
	ds_read2_b32 v[16:17], v28 offset0:99 offset1:107
	ds_read2_b32 v[18:19], v28 offset0:132 offset1:140
	ds_read2_b32 v[20:21], v28 offset0:165 offset1:173
	ds_read2_b32 v[22:23], v28 offset0:198 offset1:206
	ds_read2_b32 v[24:25], v28 offset0:231 offset1:239
	s_lshl_b32 s4, s4, 1
	s_add_u32 s4, s29, s4
	s_addc_u32 s5, s30, 0
	v_lshlrev_b32_e32 v2, 1, v4
	v_ashrrev_i32_e32 v9, 31, v8
	v_lshl_add_u64 v[26:27], s[4:5], 0, v[2:3]
	v_lshlrev_b64 v[8:9], 11, v[8:9]
	s_waitcnt lgkmcnt(6)
	v_cvt_pk_bf16_f32 v4, v12, v10
	s_waitcnt lgkmcnt(4)
	v_cvt_pk_bf16_f32 v5, v14, v16
	s_waitcnt lgkmcnt(2)
	v_cvt_pk_bf16_f32 v6, v18, v20
	s_waitcnt lgkmcnt(0)
	v_cvt_pk_bf16_f32 v7, v22, v24
	v_lshl_add_u64 v[8:9], v[26:27], 0, v[8:9]
	global_store_dwordx4 v[8:9], v[4:7], off
	v_add_co_u32_e32 v10, vcc, s59, v8
	s_nop 0
	v_cvt_pk_bf16_f32 v4, v13, v11
	v_cvt_pk_bf16_f32 v5, v15, v17
	v_cvt_pk_bf16_f32 v6, v19, v21
	v_cvt_pk_bf16_f32 v7, v23, v25
	ds_read2_b32 v[12:13], v28 offset0:49 offset1:57
	ds_read2_b32 v[14:15], v28 offset0:16 offset1:24
	ds_read2_b32 v[16:17], v28 offset0:82 offset1:90
	ds_read2_b32 v[18:19], v28 offset0:115 offset1:123
	ds_read2_b32 v[20:21], v28 offset0:148 offset1:156
	ds_read2_b32 v[22:23], v28 offset0:181 offset1:189
	ds_read2_b32 v[24:25], v28 offset0:214 offset1:222
	ds_read2_b32 v[26:27], v28 offset0:247 offset1:255
	v_addc_co_u32_e32 v11, vcc, 0, v9, vcc
	global_store_dwordx4 v[10:11], v[4:7], off
	v_add_co_u32_e32 v10, vcc, s60, v8
	s_waitcnt lgkmcnt(6)
	v_cvt_pk_bf16_f32 v4, v14, v12
	v_addc_co_u32_e32 v11, vcc, 0, v9, vcc
	s_waitcnt lgkmcnt(4)
	v_cvt_pk_bf16_f32 v5, v16, v18
	s_waitcnt lgkmcnt(2)
	v_cvt_pk_bf16_f32 v6, v20, v22
	s_waitcnt lgkmcnt(0)
	v_cvt_pk_bf16_f32 v7, v24, v26
	v_add_co_u32_e32 v8, vcc, 0xc000, v8
	global_store_dwordx4 v[10:11], v[4:7], off
	s_nop 0
	v_addc_co_u32_e32 v9, vcc, 0, v9, vcc
	v_cvt_pk_bf16_f32 v4, v15, v13
	v_cvt_pk_bf16_f32 v5, v17, v19
	v_cvt_pk_bf16_f32 v6, v21, v23
	v_cvt_pk_bf16_f32 v7, v25, v27
	global_store_dwordx4 v[8:9], v[4:7], off
	s_waitcnt lgkmcnt(0)

; #define LAS __attribute__((address_space(3)))
; __device__ __forceinline__ unsigned pk2(float lo, float hi) { f32x2 v = {lo, hi}; bf16x2_t b = __builtin_convertvector(v, bf16x2_t); return __builtin_bit_cast(unsigned, b); }
; __device__ __forceinline__ void tr_item(const float* W, int K, int N, bf16_t* WT, int ldt, int rowmode, const float* ksc, LAS float* scr, int item, int lane) {
;     const int nblk = N / 32, kb = item / nblk, nb = item % nblk, k0 = 64 * kb, n0 = 32 * nb;
; #pragma unroll 16
;     for (int i = 0; i < 32; ++i) { const int kk = 2 * i + (lane >> 5); float v = W[(size_t)(k0 + kk) * N + n0 + (lane & 31)]; if (ksc) v *= ksc[k0 + kk]; scr[kk * 33 + (lane & 31)] = v; }
;     asm volatile("s_waitcnt lgkmcnt(0)" ::: "memory");
;     const int c = lane & 7;
; #pragma unroll
;     for (int j = 0; j < 4; ++j) { const int n = n0 + (lane >> 3) + 8 * j; const LAS float* s = scr + (8 * c) * 33 + (lane >> 3) + 8 * j;
;         u32x4 o; o.x = pk2(s[0 * 33], s[1 * 33]); o.y = pk2(s[2 * 33], s[3 * 33]); o.z = pk2(s[4 * 33], s[5 * 33]); o.w = pk2(s[6 * 33], s[7 * 33]);
;         int row = n; if (rowmode) row = (n >> 7) * 256 + (n & 127) + (rowmode == 2 ? 128 : 0);
;         *(u32x4*)(WT + (size_t)row * ldt + k0 + 8 * c) = o; }
;     asm volatile("s_waitcnt lgkmcnt(0)" ::: "memory");
.LBB0_123:
	global_load_dword v100, v[10:11], off nt
	v_add_u32_e32 v15, s9, v14
	v_add_u32_e32 v16, 6, v15
	v_mad_i64_i32 v[16:17], s[10:11], v16, s64, v[4:5]
	s_add_i32 s9, s9, 32
	v_lshl_add_u64 v[10:11], v[10:11], 0, s[16:17]
	s_cmp_lg_u32 s9, 64
	global_load_dword v101, v[8:9], off nt
	v_lshl_add_u64 v[8:9], v[8:9], 0, s[16:17]
	global_load_dword v102, v[6:7], off nt
	v_lshl_add_u64 v[6:7], v[6:7], 0, s[16:17]
	global_load_dword v103, v[16:17], off nt
	v_add_u32_e32 v16, 8, v15
	v_mad_i64_i32 v[16:17], s[10:11], v16, s64, v[4:5]
	global_load_dword v104, v[16:17], off nt
	v_add_u32_e32 v16, 10, v15
	v_mad_i64_i32 v[16:17], s[10:11], v16, s64, v[4:5]
	global_load_dword v105, v[16:17], off nt
	v_add_u32_e32 v16, 12, v15
	v_mad_i64_i32 v[16:17], s[10:11], v16, s64, v[4:5]
	global_load_dword v106, v[16:17], off nt
	v_add_u32_e32 v16, 14, v15
	v_mad_i64_i32 v[16:17], s[10:11], v16, s64, v[4:5]
	global_load_dword v107, v[16:17], off nt
	v_add_u32_e32 v16, 16, v15
	v_mad_i64_i32 v[16:17], s[10:11], v16, s64, v[4:5]
	global_load_dword v108, v[16:17], off nt
	v_add_u32_e32 v16, 18, v15
	v_mad_i64_i32 v[16:17], s[10:11], v16, s64, v[4:5]
	global_load_dword v109, v[16:17], off nt
	v_add_u32_e32 v16, 20, v15
	v_mad_i64_i32 v[16:17], s[10:11], v16, s64, v[4:5]
	global_load_dword v110, v[16:17], off nt
	v_add_u32_e32 v16, 22, v15
	v_mad_i64_i32 v[16:17], s[10:11], v16, s64, v[4:5]
	global_load_dword v111, v[16:17], off nt
	v_add_u32_e32 v16, 24, v15
	v_mad_i64_i32 v[16:17], s[10:11], v16, s64, v[4:5]
	global_load_dword v112, v[16:17], off nt
	v_add_u32_e32 v16, 26, v15
	v_mad_i64_i32 v[16:17], s[10:11], v16, s64, v[4:5]
	global_load_dword v113, v[16:17], off nt
	v_add_u32_e32 v16, 28, v15
	v_mad_i64_i32 v[16:17], s[10:11], v16, s64, v[4:5]
	v_add_u32_e32 v15, 30, v15
	global_load_dword v114, v[16:17], off nt
	v_mad_i64_i32 v[16:17], s[10:11], v15, s64, v[4:5]
	global_load_dword v115, v[16:17], off nt
	s_waitcnt vmcnt(15)
	ds_write_b32 v13, v100
	s_waitcnt vmcnt(14)
	ds_write_b32 v13, v101 offset:264
	s_waitcnt vmcnt(13)
	ds_write_b32 v13, v102 offset:528
	s_waitcnt vmcnt(12)
	ds_write_b32 v13, v103 offset:792
	s_waitcnt vmcnt(11)
	ds_write_b32 v13, v104 offset:1056
	s_waitcnt vmcnt(10)
	ds_write_b32 v13, v105 offset:1320
	s_waitcnt vmcnt(9)
	ds_write_b32 v13, v106 offset:1584
	s_waitcnt vmcnt(8)
	ds_write_b32 v13, v107 offset:1848
	s_waitcnt vmcnt(7)
	ds_write_b32 v13, v108 offset:2112
	s_waitcnt vmcnt(6)
	ds_write_b32 v13, v109 offset:2376
	s_waitcnt vmcnt(5)
	ds_write_b32 v13, v110 offset:2640
	s_waitcnt vmcnt(4)
	ds_write_b32 v13, v111 offset:2904
	s_waitcnt vmcnt(3)
	ds_write_b32 v13, v112 offset:3168
	s_waitcnt vmcnt(2)
	ds_write_b32 v13, v113 offset:3432
	s_waitcnt vmcnt(1)
	ds_write_b32 v13, v114 offset:3696
	s_waitcnt vmcnt(0)
	ds_write_b32 v13, v115 offset:3960
	v_add_u32_e32 v13, 0x1080, v13
	s_cbranch_scc1 .LBB0_123
	v_lshlrev_b32_e32 v4, 3, v12
	v_ashrrev_i32_e32 v2, 3, v12
	v_and_b32_e32 v4, 56, v4
	v_add_u32_e32 v8, s8, v2
	v_mul_u32_u24_e32 v5, 0x84, v4
	v_lshlrev_b32_e32 v2, 2, v2
	s_waitcnt lgkmcnt(0)
	v_add3_u32 v28, s3, v5, v2
	ds_read2_b32 v[10:11], v28 offset0:33 offset1:41
	ds_read2_b32 v[12:13], v28 offset1:8
	ds_read2_b32 v[14:15], v28 offset0:66 offset1:74
	ds_read2_b32 v[16:17], v28 offset0:99 offset1:107
	ds_read2_b32 v[18:19], v28 offset0:132 offset1:140
	ds_read2_b32 v[20:21], v28 offset0:165 offset1:173
	ds_read2_b32 v[22:23], v28 offset0:198 offset1:206
	ds_read2_b32 v[24:25], v28 offset0:231 offset1:239
	s_lshl_b64 s[4:5], s[4:5], 1
	s_add_u32 s4, s23, s4
	s_addc_u32 s5, s24, s5
	v_lshlrev_b32_e32 v2, 1, v4
	v_ashrrev_i32_e32 v9, 31, v8
	v_lshl_add_u64 v[26:27], s[4:5], 0, v[2:3]
	v_lshlrev_b64 v[8:9], 11, v[8:9]
	s_waitcnt lgkmcnt(6)
	v_cvt_pk_bf16_f32 v4, v12, v10
	s_waitcnt lgkmcnt(4)
	v_cvt_pk_bf16_f32 v5, v14, v16
	s_waitcnt lgkmcnt(2)
	v_cvt_pk_bf16_f32 v6, v18, v20
	s_waitcnt lgkmcnt(0)
	v_cvt_pk_bf16_f32 v7, v22, v24
	v_lshl_add_u64 v[8:9], v[26:27], 0, v[8:9]
	global_store_dwordx4 v[8:9], v[4:7], off
	v_add_co_u32_e32 v10, vcc, s59, v8
	s_nop 0
	v_cvt_pk_bf16_f32 v4, v13, v11
	v_cvt_pk_bf16_f32 v5, v15, v17
	v_cvt_pk_bf16_f32 v6, v19, v21
	v_cvt_pk_bf16_f32 v7, v23, v25
	ds_read2_b32 v[12:13], v28 offset0:49 offset1:57
	ds_read2_b32 v[14:15], v28 offset0:16 offset1:24
	ds_read2_b32 v[16:17], v28 offset0:82 offset1:90
	ds_read2_b32 v[18:19], v28 offset0:115 offset1:123
	ds_read2_b32 v[20:21], v28 offset0:148 offset1:156
	ds_read2_b32 v[22:23], v28 offset0:181 offset1:189
	ds_read2_b32 v[24:25], v28 offset0:214 offset1:222
	ds_read2_b32 v[26:27], v28 offset0:247 offset1:255
	v_addc_co_u32_e32 v11, vcc, 0, v9, vcc
	global_store_dwordx4 v[10:11], v[4:7], off
	v_add_co_u32_e32 v10, vcc, s60, v8
	s_waitcnt lgkmcnt(6)
	v_cvt_pk_bf16_f32 v4, v14, v12
	v_addc_co_u32_e32 v11, vcc, 0, v9, vcc
	s_waitcnt lgkmcnt(4)
	v_cvt_pk_bf16_f32 v5, v16, v18
	s_waitcnt lgkmcnt(2)
	v_cvt_pk_bf16_f32 v6, v20, v22
	s_waitcnt lgkmcnt(0)
	v_cvt_pk_bf16_f32 v7, v24, v26
	v_add_co_u32_e32 v8, vcc, 0xc000, v8
	global_store_dwordx4 v[10:11], v[4:7], off
	s_nop 0
	v_addc_co_u32_e32 v9, vcc, 0, v9, vcc
	v_cvt_pk_bf16_f32 v4, v15, v13
	v_cvt_pk_bf16_f32 v5, v17, v19
	v_cvt_pk_bf16_f32 v6, v21, v23
	v_cvt_pk_bf16_f32 v7, v25, v27
	global_store_dwordx4 v[8:9], v[4:7], off
	s_waitcnt lgkmcnt(0)
	s_branch .LBB0_16
